# SwiGLU epilogue VALU rewritten with packed f32 mul/add (4 outputs interleaved), on top of mergewait+noprio
# baseline (speedup 1.0000x reference)
; __device__ __forceinline__ unsigned cvt_pk_bf16(float lo, float hi) { unsigned r; asm volatile("v_cvt_pk_bf16_f32 %0, %1, %2" : "=v"(r) : "v"(lo), "v"(hi)); return r; }
; __device__ __forceinline__ float silu_mul(float g, float u) { return g * u * __builtin_amdgcn_rcpf(1.0f + __builtin_amdgcn_exp2f(g * -1.4426950408889634f)); }
;     __device__ __forceinline__ void operator()(const f32x4 (&acc)[2][2][4][2], const Unit& u, int wr, int wc, int fr, int fq) const {
;     ...
;         for (int ai = 0; ai < 2; ++ai)
; #pragma unroll
;             for (int m = 0; m < 4; ++m) { bf16_t* rowp = O + (size_t)(row0 + ai * HALF + m * 16) * ldc + col0;
;                 const f32x4 g0 = acc[ai][0][m][0], g1 = acc[ai][0][m][1], u0 = acc[ai][1][m][0], u1 = acc[ai][1][m][1];
;                 u32x4 w; w.x = cvt_pk_bf16(silu_mul(g0[0], u0[0]), silu_mul(g0[1], u0[1])); w.y = cvt_pk_bf16(silu_mul(g0[2], u0[2]), silu_mul(g0[3], u0[3]));
;                 w.z = cvt_pk_bf16(silu_mul(g1[0], u1[0]), silu_mul(g1[1], u1[1])); w.w = cvt_pk_bf16(silu_mul(g1[2], u1[2]), silu_mul(g1[3], u1[3]));
;                 *(u32x4*)rowp = w; }
.LBB0_591:
	v_mov_b32_e32 v244, 0xbfb8aa3b
	v_mov_b32_e32 v245, 0xbfb8aa3b
	v_mov_b32_e32 v246, 1.0
	v_mov_b32_e32 v247, 1.0
	v_lshl_or_b32 v160, s20, 7, v169
	v_lshl_add_u32 v131, s21, 8, v163
	v_ashrrev_i32_e32 v161, 31, v160
	v_mad_i64_i32 v[164:165], s[2:3], v131, s91, v[150:151]
	v_lshlrev_b64 v[160:161], 1, v[160:161]
	v_lshl_add_u64 v[164:165], v[164:165], 0, v[160:161]
	v_pk_mul_f32 v[120:121], v[124:125], v[120:121]
	v_pk_mul_f32 v[122:123], v[126:127], v[122:123]
	v_pk_mul_f32 v[112:113], v[116:117], v[112:113]
	v_pk_mul_f32 v[114:115], v[118:119], v[114:115]
	v_pk_mul_f32 v[124:125], v[124:125], v[244:245]
	v_pk_mul_f32 v[126:127], v[126:127], v[244:245]
	v_pk_mul_f32 v[116:117], v[116:117], v[244:245]
	v_pk_mul_f32 v[118:119], v[118:119], v[244:245]
	v_exp_f32_e32 v124, v124
	v_exp_f32_e32 v125, v125
	v_exp_f32_e32 v126, v126
	v_exp_f32_e32 v127, v127
	v_exp_f32_e32 v116, v116
	v_exp_f32_e32 v117, v117
	v_exp_f32_e32 v118, v118
	v_exp_f32_e32 v119, v119
	v_pk_add_f32 v[124:125], v[124:125], v[246:247]
	v_pk_add_f32 v[126:127], v[126:127], v[246:247]
	v_pk_add_f32 v[116:117], v[116:117], v[246:247]
	v_pk_add_f32 v[118:119], v[118:119], v[246:247]
	v_rcp_f32_e32 v124, v124
	v_rcp_f32_e32 v125, v125
	v_rcp_f32_e32 v126, v126
	v_rcp_f32_e32 v127, v127
	v_rcp_f32_e32 v116, v116
	v_rcp_f32_e32 v117, v117
	v_rcp_f32_e32 v118, v118
	v_rcp_f32_e32 v119, v119
	v_pk_mul_f32 v[120:121], v[124:125], v[120:121]
	v_pk_mul_f32 v[122:123], v[126:127], v[122:123]
	v_pk_mul_f32 v[112:113], v[116:117], v[112:113]
	v_pk_mul_f32 v[114:115], v[118:119], v[114:115]
	v_cvt_pk_bf16_f32 v120, v120, v121
	v_cvt_pk_bf16_f32 v121, v122, v123
	v_cvt_pk_bf16_f32 v122, v112, v113
	v_cvt_pk_bf16_f32 v123, v114, v115
	flat_store_dwordx4 v[164:165], v[120:123]
	v_or_b32_e32 v112, 16, v131
	v_mad_i64_i32 v[112:113], s[2:3], v112, s91, v[150:151]
	v_lshl_add_u64 v[112:113], v[112:113], 0, v[160:161]
	v_pk_mul_f32 v[104:105], v[108:109], v[104:105]
	v_pk_mul_f32 v[106:107], v[110:111], v[106:107]
	v_pk_mul_f32 v[96:97], v[100:101], v[96:97]
	v_pk_mul_f32 v[98:99], v[102:103], v[98:99]
	v_pk_mul_f32 v[108:109], v[108:109], v[244:245]
	v_pk_mul_f32 v[110:111], v[110:111], v[244:245]
	v_pk_mul_f32 v[100:101], v[100:101], v[244:245]
	v_pk_mul_f32 v[102:103], v[102:103], v[244:245]
	v_exp_f32_e32 v108, v108
	v_exp_f32_e32 v109, v109
	v_exp_f32_e32 v110, v110
	v_exp_f32_e32 v111, v111
	v_exp_f32_e32 v100, v100
	v_exp_f32_e32 v101, v101
	v_exp_f32_e32 v102, v102
	v_exp_f32_e32 v103, v103
	v_pk_add_f32 v[108:109], v[108:109], v[246:247]
	v_pk_add_f32 v[110:111], v[110:111], v[246:247]
	v_pk_add_f32 v[100:101], v[100:101], v[246:247]
	v_pk_add_f32 v[102:103], v[102:103], v[246:247]
	v_rcp_f32_e32 v108, v108
	v_rcp_f32_e32 v109, v109
	v_rcp_f32_e32 v110, v110
	v_rcp_f32_e32 v111, v111
	v_rcp_f32_e32 v100, v100
	v_rcp_f32_e32 v101, v101
	v_rcp_f32_e32 v102, v102
	v_rcp_f32_e32 v103, v103
	v_pk_mul_f32 v[104:105], v[108:109], v[104:105]
	v_pk_mul_f32 v[106:107], v[110:111], v[106:107]
	v_pk_mul_f32 v[96:97], v[100:101], v[96:97]
	v_pk_mul_f32 v[98:99], v[102:103], v[98:99]
	v_cvt_pk_bf16_f32 v104, v104, v105
	v_cvt_pk_bf16_f32 v105, v106, v107
	v_cvt_pk_bf16_f32 v106, v96, v97
	v_cvt_pk_bf16_f32 v107, v98, v99
	flat_store_dwordx4 v[112:113], v[104:107]
	v_or_b32_e32 v96, 32, v131
	v_mad_i64_i32 v[96:97], s[2:3], v96, s91, v[150:151]
	v_lshl_add_u64 v[96:97], v[96:97], 0, v[160:161]
	v_pk_mul_f32 v[88:89], v[92:93], v[88:89]
	v_pk_mul_f32 v[90:91], v[94:95], v[90:91]
	v_pk_mul_f32 v[80:81], v[84:85], v[80:81]
	v_pk_mul_f32 v[82:83], v[86:87], v[82:83]
	v_pk_mul_f32 v[92:93], v[92:93], v[244:245]
	v_pk_mul_f32 v[94:95], v[94:95], v[244:245]
	v_pk_mul_f32 v[84:85], v[84:85], v[244:245]
	v_pk_mul_f32 v[86:87], v[86:87], v[244:245]
	v_exp_f32_e32 v92, v92
	v_exp_f32_e32 v93, v93
	v_exp_f32_e32 v94, v94
	v_exp_f32_e32 v95, v95
	v_exp_f32_e32 v84, v84
	v_exp_f32_e32 v85, v85
	v_exp_f32_e32 v86, v86
	v_exp_f32_e32 v87, v87
	v_pk_add_f32 v[92:93], v[92:93], v[246:247]
	v_pk_add_f32 v[94:95], v[94:95], v[246:247]
	v_pk_add_f32 v[84:85], v[84:85], v[246:247]
	v_pk_add_f32 v[86:87], v[86:87], v[246:247]
	v_rcp_f32_e32 v92, v92
	v_rcp_f32_e32 v93, v93
	v_rcp_f32_e32 v94, v94
	v_rcp_f32_e32 v95, v95
	v_rcp_f32_e32 v84, v84
	v_rcp_f32_e32 v85, v85
	v_rcp_f32_e32 v86, v86
	v_rcp_f32_e32 v87, v87
	v_pk_mul_f32 v[88:89], v[92:93], v[88:89]
	v_pk_mul_f32 v[90:91], v[94:95], v[90:91]
	v_pk_mul_f32 v[80:81], v[84:85], v[80:81]
	v_pk_mul_f32 v[82:83], v[86:87], v[82:83]
	v_cvt_pk_bf16_f32 v88, v88, v89
	v_cvt_pk_bf16_f32 v89, v90, v91
	v_cvt_pk_bf16_f32 v90, v80, v81
	v_cvt_pk_bf16_f32 v91, v82, v83
	flat_store_dwordx4 v[96:97], v[88:91]
	v_or_b32_e32 v80, 48, v131
	v_mad_i64_i32 v[80:81], s[2:3], v80, s91, v[150:151]
	v_lshl_add_u64 v[80:81], v[80:81], 0, v[160:161]
	v_pk_mul_f32 v[72:73], v[76:77], v[72:73]
	v_pk_mul_f32 v[74:75], v[78:79], v[74:75]
	v_pk_mul_f32 v[64:65], v[68:69], v[64:65]
	v_pk_mul_f32 v[66:67], v[70:71], v[66:67]
	v_pk_mul_f32 v[76:77], v[76:77], v[244:245]
	v_pk_mul_f32 v[78:79], v[78:79], v[244:245]
	v_pk_mul_f32 v[68:69], v[68:69], v[244:245]
	v_pk_mul_f32 v[70:71], v[70:71], v[244:245]
	v_exp_f32_e32 v76, v76
	v_exp_f32_e32 v77, v77
	v_exp_f32_e32 v78, v78
	v_exp_f32_e32 v79, v79
	v_exp_f32_e32 v68, v68
	v_exp_f32_e32 v69, v69
	v_exp_f32_e32 v70, v70
	v_exp_f32_e32 v71, v71
	v_pk_add_f32 v[76:77], v[76:77], v[246:247]
	v_pk_add_f32 v[78:79], v[78:79], v[246:247]
	v_pk_add_f32 v[68:69], v[68:69], v[246:247]
	v_pk_add_f32 v[70:71], v[70:71], v[246:247]
	v_rcp_f32_e32 v76, v76
	v_rcp_f32_e32 v77, v77
	v_rcp_f32_e32 v78, v78
	v_rcp_f32_e32 v79, v79
	v_rcp_f32_e32 v68, v68
; __device__ __forceinline__ unsigned cvt_pk_bf16(float lo, float hi) { unsigned r; asm volatile("v_cvt_pk_bf16_f32 %0, %1, %2" : "=v"(r) : "v"(lo), "v"(hi)); return r; }
; __device__ __forceinline__ float silu_mul(float g, float u) { return g * u * __builtin_amdgcn_rcpf(1.0f + __builtin_amdgcn_exp2f(g * -1.4426950408889634f)); }
;     __device__ __forceinline__ void operator()(const f32x4 (&acc)[2][2][4][2], const Unit& u, int wr, int wc, int fr, int fq) const {
;     ...
;         for (int ai = 0; ai < 2; ++ai)
; #pragma unroll
;             for (int m = 0; m < 4; ++m) { bf16_t* rowp = O + (size_t)(row0 + ai * HALF + m * 16) * ldc + col0;
;                 const f32x4 g0 = acc[ai][0][m][0], g1 = acc[ai][0][m][1], u0 = acc[ai][1][m][0], u1 = acc[ai][1][m][1];
;                 u32x4 w; w.x = cvt_pk_bf16(silu_mul(g0[0], u0[0]), silu_mul(g0[1], u0[1])); w.y = cvt_pk_bf16(silu_mul(g0[2], u0[2]), silu_mul(g0[3], u0[3]));
;                 w.z = cvt_pk_bf16(silu_mul(g1[0], u1[0]), silu_mul(g1[1], u1[1])); w.w = cvt_pk_bf16(silu_mul(g1[2], u1[2]), silu_mul(g1[3], u1[3]));
;                 *(u32x4*)rowp = w; }
	v_rcp_f32_e32 v69, v69
	v_rcp_f32_e32 v70, v70
	v_rcp_f32_e32 v71, v71
	v_pk_mul_f32 v[72:73], v[76:77], v[72:73]
	v_pk_mul_f32 v[74:75], v[78:79], v[74:75]
	v_pk_mul_f32 v[64:65], v[68:69], v[64:65]
	v_pk_mul_f32 v[66:67], v[70:71], v[66:67]
	v_cvt_pk_bf16_f32 v72, v72, v73
	v_cvt_pk_bf16_f32 v73, v74, v75
	v_cvt_pk_bf16_f32 v74, v64, v65
	v_cvt_pk_bf16_f32 v75, v66, v67
	flat_store_dwordx4 v[80:81], v[72:75]
	v_add_u32_e32 v64, 0x80, v131
	v_mad_i64_i32 v[64:65], s[2:3], v64, s91, v[150:151]
	v_lshl_add_u64 v[64:65], v[64:65], 0, v[160:161]
	v_pk_mul_f32 v[56:57], v[60:61], v[56:57]
	v_pk_mul_f32 v[58:59], v[62:63], v[58:59]
	v_pk_mul_f32 v[48:49], v[52:53], v[48:49]
	v_pk_mul_f32 v[50:51], v[54:55], v[50:51]
	v_pk_mul_f32 v[60:61], v[60:61], v[244:245]
	v_pk_mul_f32 v[62:63], v[62:63], v[244:245]
	v_pk_mul_f32 v[52:53], v[52:53], v[244:245]
	v_pk_mul_f32 v[54:55], v[54:55], v[244:245]
	v_exp_f32_e32 v60, v60
	v_exp_f32_e32 v61, v61
	v_exp_f32_e32 v62, v62
	v_exp_f32_e32 v63, v63
	v_exp_f32_e32 v52, v52
	v_exp_f32_e32 v53, v53
	v_exp_f32_e32 v54, v54
	v_exp_f32_e32 v55, v55
	v_pk_add_f32 v[60:61], v[60:61], v[246:247]
	v_pk_add_f32 v[62:63], v[62:63], v[246:247]
	v_pk_add_f32 v[52:53], v[52:53], v[246:247]
	v_pk_add_f32 v[54:55], v[54:55], v[246:247]
	v_rcp_f32_e32 v60, v60
	v_rcp_f32_e32 v61, v61
	v_rcp_f32_e32 v62, v62
	v_rcp_f32_e32 v63, v63
	v_rcp_f32_e32 v52, v52
	v_rcp_f32_e32 v53, v53
	v_rcp_f32_e32 v54, v54
	v_rcp_f32_e32 v55, v55
	v_pk_mul_f32 v[56:57], v[60:61], v[56:57]
	v_pk_mul_f32 v[58:59], v[62:63], v[58:59]
	v_pk_mul_f32 v[48:49], v[52:53], v[48:49]
	v_pk_mul_f32 v[50:51], v[54:55], v[50:51]
	v_cvt_pk_bf16_f32 v56, v56, v57
	v_cvt_pk_bf16_f32 v57, v58, v59
	v_cvt_pk_bf16_f32 v58, v48, v49
	v_cvt_pk_bf16_f32 v59, v50, v51
	flat_store_dwordx4 v[64:65], v[56:59]
	v_add_u32_e32 v48, 0x90, v131
	v_mad_i64_i32 v[48:49], s[2:3], v48, s91, v[150:151]
	v_lshl_add_u64 v[48:49], v[48:49], 0, v[160:161]
	v_pk_mul_f32 v[40:41], v[44:45], v[40:41]
	v_pk_mul_f32 v[42:43], v[46:47], v[42:43]
	v_pk_mul_f32 v[32:33], v[36:37], v[32:33]
	v_pk_mul_f32 v[34:35], v[38:39], v[34:35]
	v_pk_mul_f32 v[44:45], v[44:45], v[244:245]
	v_pk_mul_f32 v[46:47], v[46:47], v[244:245]
	v_pk_mul_f32 v[36:37], v[36:37], v[244:245]
	v_pk_mul_f32 v[38:39], v[38:39], v[244:245]
	v_exp_f32_e32 v44, v44
	v_exp_f32_e32 v45, v45
	v_exp_f32_e32 v46, v46
	v_exp_f32_e32 v47, v47
	v_exp_f32_e32 v36, v36
	v_exp_f32_e32 v37, v37
	v_exp_f32_e32 v38, v38
	v_exp_f32_e32 v39, v39
	v_pk_add_f32 v[44:45], v[44:45], v[246:247]
	v_pk_add_f32 v[46:47], v[46:47], v[246:247]
	v_pk_add_f32 v[36:37], v[36:37], v[246:247]
	v_pk_add_f32 v[38:39], v[38:39], v[246:247]
	v_rcp_f32_e32 v44, v44
	v_rcp_f32_e32 v45, v45
	v_rcp_f32_e32 v46, v46
	v_rcp_f32_e32 v47, v47
	v_rcp_f32_e32 v36, v36
	v_rcp_f32_e32 v37, v37
	v_rcp_f32_e32 v38, v38
	v_rcp_f32_e32 v39, v39
	v_pk_mul_f32 v[40:41], v[44:45], v[40:41]
	v_pk_mul_f32 v[42:43], v[46:47], v[42:43]
	v_pk_mul_f32 v[32:33], v[36:37], v[32:33]
	v_pk_mul_f32 v[34:35], v[38:39], v[34:35]
	v_cvt_pk_bf16_f32 v40, v40, v41
	v_cvt_pk_bf16_f32 v41, v42, v43
	v_cvt_pk_bf16_f32 v42, v32, v33
	v_cvt_pk_bf16_f32 v43, v34, v35
	flat_store_dwordx4 v[48:49], v[40:43]
	v_add_u32_e32 v32, 0xa0, v131
	v_mad_i64_i32 v[32:33], s[2:3], v32, s91, v[150:151]
	v_lshl_add_u64 v[32:33], v[32:33], 0, v[160:161]
	v_pk_mul_f32 v[24:25], v[28:29], v[24:25]
	v_pk_mul_f32 v[26:27], v[30:31], v[26:27]
	v_pk_mul_f32 v[16:17], v[20:21], v[16:17]
	v_pk_mul_f32 v[18:19], v[22:23], v[18:19]
	v_pk_mul_f32 v[28:29], v[28:29], v[244:245]
	v_pk_mul_f32 v[30:31], v[30:31], v[244:245]
	v_pk_mul_f32 v[20:21], v[20:21], v[244:245]
	v_pk_mul_f32 v[22:23], v[22:23], v[244:245]
	v_exp_f32_e32 v28, v28
	v_exp_f32_e32 v29, v29
	v_exp_f32_e32 v30, v30
	v_exp_f32_e32 v31, v31
	v_exp_f32_e32 v20, v20
	v_exp_f32_e32 v21, v21
	v_exp_f32_e32 v22, v22
	v_exp_f32_e32 v23, v23
	v_pk_add_f32 v[28:29], v[28:29], v[246:247]
	v_pk_add_f32 v[30:31], v[30:31], v[246:247]
	v_pk_add_f32 v[20:21], v[20:21], v[246:247]
	v_pk_add_f32 v[22:23], v[22:23], v[246:247]
	v_rcp_f32_e32 v28, v28
	v_rcp_f32_e32 v29, v29
	v_rcp_f32_e32 v30, v30
	v_rcp_f32_e32 v31, v31
	v_rcp_f32_e32 v20, v20
	v_rcp_f32_e32 v21, v21
	v_rcp_f32_e32 v22, v22
	v_rcp_f32_e32 v23, v23
	v_pk_mul_f32 v[24:25], v[28:29], v[24:25]
	v_pk_mul_f32 v[26:27], v[30:31], v[26:27]
	v_pk_mul_f32 v[16:17], v[20:21], v[16:17]
	v_pk_mul_f32 v[18:19], v[22:23], v[18:19]
	v_cvt_pk_bf16_f32 v24, v24, v25
	v_cvt_pk_bf16_f32 v25, v26, v27
	v_cvt_pk_bf16_f32 v26, v16, v17
	v_cvt_pk_bf16_f32 v27, v18, v19
	flat_store_dwordx4 v[32:33], v[24:27]
	v_add_u32_e32 v16, 0xb0, v131
	v_mad_i64_i32 v[16:17], s[2:3], v16, s91, v[150:151]
	v_lshl_add_u64 v[16:17], v[16:17], 0, v[160:161]
	s_mov_b64 s[2:3], -1
	s_andn2_b64 vcc, exec, s[4:5]
	v_pk_mul_f32 v[8:9], v[12:13], v[8:9]
	v_pk_mul_f32 v[10:11], v[14:15], v[10:11]
	v_pk_mul_f32 v[0:1], v[4:5], v[0:1]
	v_pk_mul_f32 v[2:3], v[6:7], v[2:3]
	v_pk_mul_f32 v[12:13], v[12:13], v[244:245]
	v_pk_mul_f32 v[14:15], v[14:15], v[244:245]
	v_pk_mul_f32 v[4:5], v[4:5], v[244:245]
	v_pk_mul_f32 v[6:7], v[6:7], v[244:245]
	v_exp_f32_e32 v12, v12
	v_exp_f32_e32 v13, v13
	v_exp_f32_e32 v14, v14
	v_exp_f32_e32 v15, v15
	v_exp_f32_e32 v4, v4
	v_exp_f32_e32 v5, v5
	v_exp_f32_e32 v6, v6
	v_exp_f32_e32 v7, v7
	v_pk_add_f32 v[12:13], v[12:13], v[246:247]
	v_pk_add_f32 v[14:15], v[14:15], v[246:247]
	v_pk_add_f32 v[4:5], v[4:5], v[246:247]
	v_pk_add_f32 v[6:7], v[6:7], v[246:247]
	v_rcp_f32_e32 v12, v12
	v_rcp_f32_e32 v13, v13
	v_rcp_f32_e32 v14, v14
	v_rcp_f32_e32 v15, v15
	v_rcp_f32_e32 v4, v4
	v_rcp_f32_e32 v5, v5
	v_rcp_f32_e32 v6, v6
	v_rcp_f32_e32 v7, v7
	v_pk_mul_f32 v[8:9], v[12:13], v[8:9]
	v_pk_mul_f32 v[10:11], v[14:15], v[10:11]
	v_pk_mul_f32 v[0:1], v[4:5], v[0:1]
	v_pk_mul_f32 v[2:3], v[6:7], v[2:3]
	v_cvt_pk_bf16_f32 v8, v8, v9
	v_cvt_pk_bf16_f32 v9, v10, v11
	v_cvt_pk_bf16_f32 v10, v0, v1
	v_cvt_pk_bf16_f32 v11, v2, v3
	flat_store_dwordx4 v[16:17], v[8:11]
	s_cbranch_vccnz .LBB0_584
	s_andn2_b64 vcc, exec, s[6:7]
	s_cbranch_vccnz .LBB0_583
	s_barrier
	s_branch .LBB0_583
